# indexer canonicalize removal + phase-B tail job rebalance + S5 prefix loads batched 16 deep
# speedup vs baseline: 1.0073x; 1.0073x over previous
.LBB0_227:
	s_cmpk_lg_i32 s92, 0x200
	s_cbranch_scc1 .Ltb_orig
	s_cmpk_lt_i32 s33, 0x1000
	s_cbranch_scc1 .Ltb_orig
	s_cmpk_lt_i32 s33, 0x1040
	s_cbranch_scc1 .LBB0_387
	s_addk_i32 s33, 0x1c0
	s_addk_i32 s2, 0x1c0
	s_branch .Ltb_chk

.Ltb_chk:
	s_cmpk_lt_i32 s33, 0x1b80
	s_cbranch_scc0 .LBB0_387

.LBB0_517:
	v_lshl_add_u32 v4, s39, 2, v187
	v_and_b32_e32 v0, 63, v4
	v_lshlrev_b32_e32 v124, 12, v0
	v_lshlrev_b32_e32 v7, 4, v0
	v_lshl_or_b32 v5, v0, 6, v129
	v_or_b32_e32 v6, v7, v175
	v_lshlrev_b32_e32 v2, 13, v0
	v_mov_b32_e32 v3, v125
	v_lshl_add_u64 v[0:1], v[136:137], 0, v[124:125]
	global_load_dwordx4 v[64:67], v[0:1], off
	global_load_dwordx4 v[68:71], v[0:1], off offset:1024
	global_load_dwordx4 v[72:75], v[0:1], off offset:2048
	global_load_dwordx4 v[76:79], v[0:1], off offset:3072
	v_lshlrev_b32_e32 v1, 2, v6
	v_lshl_add_u64 v[2:3], v[126:127], 0, v[2:3]
	v_lshlrev_b32_e32 v0, 3, v5
	global_load_dword v8, v1, s[82:83]
	global_load_dwordx4 v[80:83], v[2:3], off
	global_load_dwordx4 v[84:87], v[2:3], off offset:32
	global_load_dwordx4 v[88:91], v[2:3], off offset:64
	global_load_dwordx4 v[92:95], v[2:3], off offset:96
	global_load_dwordx4 v[96:99], v[2:3], off offset:128
	global_load_dwordx4 v[100:103], v[2:3], off offset:160
	global_load_dwordx4 v[104:107], v[2:3], off offset:192
	global_load_dwordx4 v[108:111], v[2:3], off offset:224
	global_load_dwordx2 v[142:143], v0, s[24:25]
	v_ashrrev_i32_e32 v9, 6, v4
	v_mov_b32_e32 v124, v125
	v_cmp_lt_i32_e32 vcc, 0, v9
	v_mov_b64_e32 v[150:151], v[124:125]
	s_and_saveexec_b64 s[34:35], vcc
	s_cbranch_execz .LBB0_521
	global_load_dwordx2 v[0:1], v0, s[28:29]
	v_and_b32_e32 v2, 63, v131
	v_lshlrev_b32_e32 v124, 9, v2
	v_mov_b32_e32 v150, 0
	v_lshl_add_u64 v[2:3], v[138:139], 0, v[124:125]
	v_mov_b32_e32 v6, 0
	v_readfirstlane_b32 s36, v9
	global_load_dwordx2 v[18:19], v[2:3], off
	v_lshl_add_u64 v[2:3], v[2:3], 0, s[30:31]
	global_load_dwordx2 v[20:21], v[2:3], off
	v_lshl_add_u64 v[2:3], v[2:3], 0, s[30:31]
	global_load_dwordx2 v[22:23], v[2:3], off
	v_lshl_add_u64 v[2:3], v[2:3], 0, s[30:31]
	global_load_dwordx2 v[24:25], v[2:3], off
	v_lshl_add_u64 v[2:3], v[2:3], 0, s[30:31]
	global_load_dwordx2 v[26:27], v[2:3], off
	v_lshl_add_u64 v[2:3], v[2:3], 0, s[30:31]
	global_load_dwordx2 v[28:29], v[2:3], off
	v_lshl_add_u64 v[2:3], v[2:3], 0, s[30:31]
	global_load_dwordx2 v[30:31], v[2:3], off
	v_lshl_add_u64 v[2:3], v[2:3], 0, s[30:31]
	global_load_dwordx2 v[32:33], v[2:3], off
	v_lshl_add_u64 v[2:3], v[2:3], 0, s[30:31]
	global_load_dwordx2 v[34:35], v[2:3], off
	v_lshl_add_u64 v[2:3], v[2:3], 0, s[30:31]
	global_load_dwordx2 v[36:37], v[2:3], off
	v_lshl_add_u64 v[2:3], v[2:3], 0, s[30:31]
	global_load_dwordx2 v[38:39], v[2:3], off
	v_lshl_add_u64 v[2:3], v[2:3], 0, s[30:31]
	global_load_dwordx2 v[40:41], v[2:3], off
	v_lshl_add_u64 v[2:3], v[2:3], 0, s[30:31]
	global_load_dwordx2 v[42:43], v[2:3], off
	v_lshl_add_u64 v[2:3], v[2:3], 0, s[30:31]
	global_load_dwordx2 v[44:45], v[2:3], off
	v_lshl_add_u64 v[2:3], v[2:3], 0, s[30:31]
	global_load_dwordx2 v[46:47], v[2:3], off
	v_lshl_add_u64 v[2:3], v[2:3], 0, s[30:31]
	global_load_dwordx2 v[48:49], v[2:3], off
	v_lshl_add_u64 v[2:3], v[2:3], 0, s[30:31]
	s_waitcnt vmcnt(16)
	v_pk_mov_b32 v[4:5], v[0:1], v[0:1] op_sel:[1,0]
	s_waitcnt vmcnt(15)
	v_pk_mul_f32 v[14:15], v[4:5], v[6:7] op_sel_hi:[1,0]
	v_pk_fma_f32 v[16:17], v[0:1], v[150:151], v[14:15] neg_lo:[0,0,1] neg_hi:[0,0,1]
	v_pk_fma_f32 v[14:15], v[0:1], v[150:151], v[14:15] op_sel_hi:[1,0,1]
	v_mov_b32_e32 v17, v15
	v_pk_add_f32 v[150:151], v[16:17], v[18:19]
	s_nop 0
	v_mov_b32_e32 v6, v151
	s_cmp_le_u32 s36, 1
	s_cbranch_scc1 .Ls5p_done_a
	s_waitcnt vmcnt(14)
	v_pk_mul_f32 v[14:15], v[4:5], v[6:7] op_sel_hi:[1,0]
	v_pk_fma_f32 v[16:17], v[0:1], v[150:151], v[14:15] neg_lo:[0,0,1] neg_hi:[0,0,1]
	v_pk_fma_f32 v[14:15], v[0:1], v[150:151], v[14:15] op_sel_hi:[1,0,1]
	v_mov_b32_e32 v17, v15
	v_pk_add_f32 v[150:151], v[16:17], v[20:21]
	s_nop 0
	v_mov_b32_e32 v6, v151
	s_cmp_le_u32 s36, 2
	s_cbranch_scc1 .Ls5p_done_a
	s_waitcnt vmcnt(13)
	v_pk_mul_f32 v[14:15], v[4:5], v[6:7] op_sel_hi:[1,0]
	v_pk_fma_f32 v[16:17], v[0:1], v[150:151], v[14:15] neg_lo:[0,0,1] neg_hi:[0,0,1]
	v_pk_fma_f32 v[14:15], v[0:1], v[150:151], v[14:15] op_sel_hi:[1,0,1]
	v_mov_b32_e32 v17, v15
	v_pk_add_f32 v[150:151], v[16:17], v[22:23]
	s_nop 0
	v_mov_b32_e32 v6, v151
	s_cmp_le_u32 s36, 3
	s_cbranch_scc1 .Ls5p_done_a
	s_waitcnt vmcnt(12)
	v_pk_mul_f32 v[14:15], v[4:5], v[6:7] op_sel_hi:[1,0]
	v_pk_fma_f32 v[16:17], v[0:1], v[150:151], v[14:15] neg_lo:[0,0,1] neg_hi:[0,0,1]
	v_pk_fma_f32 v[14:15], v[0:1], v[150:151], v[14:15] op_sel_hi:[1,0,1]
	v_mov_b32_e32 v17, v15
	v_pk_add_f32 v[150:151], v[16:17], v[24:25]
	s_nop 0
	v_mov_b32_e32 v6, v151
	s_cmp_le_u32 s36, 4
	s_cbranch_scc1 .Ls5p_done_a
	s_waitcnt vmcnt(11)
	v_pk_mul_f32 v[14:15], v[4:5], v[6:7] op_sel_hi:[1,0]
	v_pk_fma_f32 v[16:17], v[0:1], v[150:151], v[14:15] neg_lo:[0,0,1] neg_hi:[0,0,1]
	v_pk_fma_f32 v[14:15], v[0:1], v[150:151], v[14:15] op_sel_hi:[1,0,1]
	v_mov_b32_e32 v17, v15
	v_pk_add_f32 v[150:151], v[16:17], v[26:27]
	s_nop 0
	v_mov_b32_e32 v6, v151
	s_cmp_le_u32 s36, 5
	s_cbranch_scc1 .Ls5p_done_a
	s_waitcnt vmcnt(10)
	v_pk_mul_f32 v[14:15], v[4:5], v[6:7] op_sel_hi:[1,0]
	v_pk_fma_f32 v[16:17], v[0:1], v[150:151], v[14:15] neg_lo:[0,0,1] neg_hi:[0,0,1]
	v_pk_fma_f32 v[14:15], v[0:1], v[150:151], v[14:15] op_sel_hi:[1,0,1]
	v_mov_b32_e32 v17, v15
	v_pk_add_f32 v[150:151], v[16:17], v[28:29]
	s_nop 0
	v_mov_b32_e32 v6, v151
	s_cmp_le_u32 s36, 6
	s_cbranch_scc1 .Ls5p_done_a
	s_waitcnt vmcnt(9)
	v_pk_mul_f32 v[14:15], v[4:5], v[6:7] op_sel_hi:[1,0]
	v_pk_fma_f32 v[16:17], v[0:1], v[150:151], v[14:15] neg_lo:[0,0,1] neg_hi:[0,0,1]
	v_pk_fma_f32 v[14:15], v[0:1], v[150:151], v[14:15] op_sel_hi:[1,0,1]
	v_mov_b32_e32 v17, v15
	v_pk_add_f32 v[150:151], v[16:17], v[30:31]
	s_nop 0
	v_mov_b32_e32 v6, v151
	s_cmp_le_u32 s36, 7
	s_cbranch_scc1 .Ls5p_done_a
	s_waitcnt vmcnt(8)
	v_pk_mul_f32 v[14:15], v[4:5], v[6:7] op_sel_hi:[1,0]
	v_pk_fma_f32 v[16:17], v[0:1], v[150:151], v[14:15] neg_lo:[0,0,1] neg_hi:[0,0,1]
	v_pk_fma_f32 v[14:15], v[0:1], v[150:151], v[14:15] op_sel_hi:[1,0,1]
	v_mov_b32_e32 v17, v15
	v_pk_add_f32 v[150:151], v[16:17], v[32:33]
	s_nop 0
	v_mov_b32_e32 v6, v151
	s_cmp_le_u32 s36, 8
	s_cbranch_scc1 .Ls5p_done_a
	s_waitcnt vmcnt(7)
	v_pk_mul_f32 v[14:15], v[4:5], v[6:7] op_sel_hi:[1,0]
	v_pk_fma_f32 v[16:17], v[0:1], v[150:151], v[14:15] neg_lo:[0,0,1] neg_hi:[0,0,1]
	v_pk_fma_f32 v[14:15], v[0:1], v[150:151], v[14:15] op_sel_hi:[1,0,1]
	v_mov_b32_e32 v17, v15
	v_pk_add_f32 v[150:151], v[16:17], v[34:35]
	s_nop 0
	v_mov_b32_e32 v6, v151
	s_cmp_le_u32 s36, 9
	s_cbranch_scc1 .Ls5p_done_a
	s_waitcnt vmcnt(6)
	v_pk_mul_f32 v[14:15], v[4:5], v[6:7] op_sel_hi:[1,0]
	v_pk_fma_f32 v[16:17], v[0:1], v[150:151], v[14:15] neg_lo:[0,0,1] neg_hi:[0,0,1]
	v_pk_fma_f32 v[14:15], v[0:1], v[150:151], v[14:15] op_sel_hi:[1,0,1]
	v_mov_b32_e32 v17, v15
	v_pk_add_f32 v[150:151], v[16:17], v[36:37]
	s_nop 0
	v_mov_b32_e32 v6, v151
	s_cmp_le_u32 s36, 10
	s_cbranch_scc1 .Ls5p_done_a
	s_waitcnt vmcnt(5)
	v_pk_mul_f32 v[14:15], v[4:5], v[6:7] op_sel_hi:[1,0]
	v_pk_fma_f32 v[16:17], v[0:1], v[150:151], v[14:15] neg_lo:[0,0,1] neg_hi:[0,0,1]
	v_pk_fma_f32 v[14:15], v[0:1], v[150:151], v[14:15] op_sel_hi:[1,0,1]
	v_mov_b32_e32 v17, v15
	v_pk_add_f32 v[150:151], v[16:17], v[38:39]
	s_nop 0
	v_mov_b32_e32 v6, v151
	s_cmp_le_u32 s36, 11
	s_cbranch_scc1 .Ls5p_done_a
	s_waitcnt vmcnt(4)
	v_pk_mul_f32 v[14:15], v[4:5], v[6:7] op_sel_hi:[1,0]
	v_pk_fma_f32 v[16:17], v[0:1], v[150:151], v[14:15] neg_lo:[0,0,1] neg_hi:[0,0,1]
	v_pk_fma_f32 v[14:15], v[0:1], v[150:151], v[14:15] op_sel_hi:[1,0,1]
	v_mov_b32_e32 v17, v15
	v_pk_add_f32 v[150:151], v[16:17], v[40:41]
	s_nop 0
	v_mov_b32_e32 v6, v151
	s_cmp_le_u32 s36, 12
	s_cbranch_scc1 .Ls5p_done_a
	s_waitcnt vmcnt(3)
	v_pk_mul_f32 v[14:15], v[4:5], v[6:7] op_sel_hi:[1,0]
	v_pk_fma_f32 v[16:17], v[0:1], v[150:151], v[14:15] neg_lo:[0,0,1] neg_hi:[0,0,1]
	v_pk_fma_f32 v[14:15], v[0:1], v[150:151], v[14:15] op_sel_hi:[1,0,1]
	v_mov_b32_e32 v17, v15
	v_pk_add_f32 v[150:151], v[16:17], v[42:43]
	s_nop 0
	v_mov_b32_e32 v6, v151
	s_cmp_le_u32 s36, 13
	s_cbranch_scc1 .Ls5p_done_a
	s_waitcnt vmcnt(2)
	v_pk_mul_f32 v[14:15], v[4:5], v[6:7] op_sel_hi:[1,0]
	v_pk_fma_f32 v[16:17], v[0:1], v[150:151], v[14:15] neg_lo:[0,0,1] neg_hi:[0,0,1]
	v_pk_fma_f32 v[14:15], v[0:1], v[150:151], v[14:15] op_sel_hi:[1,0,1]
	v_mov_b32_e32 v17, v15
	v_pk_add_f32 v[150:151], v[16:17], v[44:45]
	s_nop 0
	v_mov_b32_e32 v6, v151
	s_cmp_le_u32 s36, 14
	s_cbranch_scc1 .Ls5p_done_a
	s_waitcnt vmcnt(1)
	v_pk_mul_f32 v[14:15], v[4:5], v[6:7] op_sel_hi:[1,0]
	v_pk_fma_f32 v[16:17], v[0:1], v[150:151], v[14:15] neg_lo:[0,0,1] neg_hi:[0,0,1]
	v_pk_fma_f32 v[14:15], v[0:1], v[150:151], v[14:15] op_sel_hi:[1,0,1]
	v_mov_b32_e32 v17, v15
	v_pk_add_f32 v[150:151], v[16:17], v[46:47]
	s_nop 0
	v_mov_b32_e32 v6, v151
	s_cmp_le_u32 s36, 15
	s_cbranch_scc1 .Ls5p_done_a
	s_waitcnt vmcnt(0)
	v_pk_mul_f32 v[14:15], v[4:5], v[6:7] op_sel_hi:[1,0]
	v_pk_fma_f32 v[16:17], v[0:1], v[150:151], v[14:15] neg_lo:[0,0,1] neg_hi:[0,0,1]
	v_pk_fma_f32 v[14:15], v[0:1], v[150:151], v[14:15] op_sel_hi:[1,0,1]
	v_mov_b32_e32 v17, v15
	v_pk_add_f32 v[150:151], v[16:17], v[48:49]
	s_nop 0
	v_mov_b32_e32 v6, v151
	s_cmp_le_u32 s36, 16
	s_cbranch_scc1 .Ls5p_done_a
	global_load_dwordx2 v[18:19], v[2:3], off
	v_lshl_add_u64 v[2:3], v[2:3], 0, s[30:31]
	global_load_dwordx2 v[20:21], v[2:3], off
	v_lshl_add_u64 v[2:3], v[2:3], 0, s[30:31]
	global_load_dwordx2 v[22:23], v[2:3], off
	v_lshl_add_u64 v[2:3], v[2:3], 0, s[30:31]
	global_load_dwordx2 v[24:25], v[2:3], off
	v_lshl_add_u64 v[2:3], v[2:3], 0, s[30:31]
	global_load_dwordx2 v[26:27], v[2:3], off
	v_lshl_add_u64 v[2:3], v[2:3], 0, s[30:31]
	global_load_dwordx2 v[28:29], v[2:3], off
	v_lshl_add_u64 v[2:3], v[2:3], 0, s[30:31]
	global_load_dwordx2 v[30:31], v[2:3], off
	v_lshl_add_u64 v[2:3], v[2:3], 0, s[30:31]
	global_load_dwordx2 v[32:33], v[2:3], off
	v_lshl_add_u64 v[2:3], v[2:3], 0, s[30:31]
	global_load_dwordx2 v[34:35], v[2:3], off
	v_lshl_add_u64 v[2:3], v[2:3], 0, s[30:31]
	global_load_dwordx2 v[36:37], v[2:3], off
	v_lshl_add_u64 v[2:3], v[2:3], 0, s[30:31]
	global_load_dwordx2 v[38:39], v[2:3], off
	v_lshl_add_u64 v[2:3], v[2:3], 0, s[30:31]
	global_load_dwordx2 v[40:41], v[2:3], off
	v_lshl_add_u64 v[2:3], v[2:3], 0, s[30:31]
	global_load_dwordx2 v[42:43], v[2:3], off
	v_lshl_add_u64 v[2:3], v[2:3], 0, s[30:31]
	global_load_dwordx2 v[44:45], v[2:3], off
	v_lshl_add_u64 v[2:3], v[2:3], 0, s[30:31]
	global_load_dwordx2 v[46:47], v[2:3], off
	v_lshl_add_u64 v[2:3], v[2:3], 0, s[30:31]
	global_load_dwordx2 v[48:49], v[2:3], off
	v_lshl_add_u64 v[2:3], v[2:3], 0, s[30:31]
	s_cmp_le_u32 s36, 16
	s_cbranch_scc1 .Ls5p_done_a
	s_waitcnt vmcnt(15)
	v_pk_mul_f32 v[14:15], v[4:5], v[6:7] op_sel_hi:[1,0]
	v_pk_fma_f32 v[16:17], v[0:1], v[150:151], v[14:15] neg_lo:[0,0,1] neg_hi:[0,0,1]
	v_pk_fma_f32 v[14:15], v[0:1], v[150:151], v[14:15] op_sel_hi:[1,0,1]
	v_mov_b32_e32 v17, v15
	v_pk_add_f32 v[150:151], v[16:17], v[18:19]
	s_nop 0
	v_mov_b32_e32 v6, v151
	s_cmp_le_u32 s36, 17
	s_cbranch_scc1 .Ls5p_done_a
	s_waitcnt vmcnt(14)
	v_pk_mul_f32 v[14:15], v[4:5], v[6:7] op_sel_hi:[1,0]
	v_pk_fma_f32 v[16:17], v[0:1], v[150:151], v[14:15] neg_lo:[0,0,1] neg_hi:[0,0,1]
	v_pk_fma_f32 v[14:15], v[0:1], v[150:151], v[14:15] op_sel_hi:[1,0,1]
	v_mov_b32_e32 v17, v15
	v_pk_add_f32 v[150:151], v[16:17], v[20:21]
	s_nop 0
	v_mov_b32_e32 v6, v151
	s_cmp_le_u32 s36, 18
	s_cbranch_scc1 .Ls5p_done_a
	s_waitcnt vmcnt(13)
	v_pk_mul_f32 v[14:15], v[4:5], v[6:7] op_sel_hi:[1,0]
	v_pk_fma_f32 v[16:17], v[0:1], v[150:151], v[14:15] neg_lo:[0,0,1] neg_hi:[0,0,1]
	v_pk_fma_f32 v[14:15], v[0:1], v[150:151], v[14:15] op_sel_hi:[1,0,1]
	v_mov_b32_e32 v17, v15
	v_pk_add_f32 v[150:151], v[16:17], v[22:23]
	s_nop 0
	v_mov_b32_e32 v6, v151
	s_cmp_le_u32 s36, 19
	s_cbranch_scc1 .Ls5p_done_a
	s_waitcnt vmcnt(12)
	v_pk_mul_f32 v[14:15], v[4:5], v[6:7] op_sel_hi:[1,0]
	v_pk_fma_f32 v[16:17], v[0:1], v[150:151], v[14:15] neg_lo:[0,0,1] neg_hi:[0,0,1]
	v_pk_fma_f32 v[14:15], v[0:1], v[150:151], v[14:15] op_sel_hi:[1,0,1]
	v_mov_b32_e32 v17, v15
	v_pk_add_f32 v[150:151], v[16:17], v[24:25]
	s_nop 0
	v_mov_b32_e32 v6, v151
	s_cmp_le_u32 s36, 20
	s_cbranch_scc1 .Ls5p_done_a
	s_waitcnt vmcnt(11)
	v_pk_mul_f32 v[14:15], v[4:5], v[6:7] op_sel_hi:[1,0]
	v_pk_fma_f32 v[16:17], v[0:1], v[150:151], v[14:15] neg_lo:[0,0,1] neg_hi:[0,0,1]
	v_pk_fma_f32 v[14:15], v[0:1], v[150:151], v[14:15] op_sel_hi:[1,0,1]
	v_mov_b32_e32 v17, v15
	v_pk_add_f32 v[150:151], v[16:17], v[26:27]
	s_nop 0
	v_mov_b32_e32 v6, v151
	s_cmp_le_u32 s36, 21
	s_cbranch_scc1 .Ls5p_done_a
	s_waitcnt vmcnt(10)
	v_pk_mul_f32 v[14:15], v[4:5], v[6:7] op_sel_hi:[1,0]
	v_pk_fma_f32 v[16:17], v[0:1], v[150:151], v[14:15] neg_lo:[0,0,1] neg_hi:[0,0,1]
	v_pk_fma_f32 v[14:15], v[0:1], v[150:151], v[14:15] op_sel_hi:[1,0,1]
	v_mov_b32_e32 v17, v15
	v_pk_add_f32 v[150:151], v[16:17], v[28:29]
	s_nop 0
	v_mov_b32_e32 v6, v151
	s_cmp_le_u32 s36, 22
	s_cbranch_scc1 .Ls5p_done_a
	s_waitcnt vmcnt(9)
	v_pk_mul_f32 v[14:15], v[4:5], v[6:7] op_sel_hi:[1,0]
	v_pk_fma_f32 v[16:17], v[0:1], v[150:151], v[14:15] neg_lo:[0,0,1] neg_hi:[0,0,1]
	v_pk_fma_f32 v[14:15], v[0:1], v[150:151], v[14:15] op_sel_hi:[1,0,1]
	v_mov_b32_e32 v17, v15
	v_pk_add_f32 v[150:151], v[16:17], v[30:31]
	s_nop 0
	v_mov_b32_e32 v6, v151
	s_cmp_le_u32 s36, 23
	s_cbranch_scc1 .Ls5p_done_a
	s_waitcnt vmcnt(8)
	v_pk_mul_f32 v[14:15], v[4:5], v[6:7] op_sel_hi:[1,0]
	v_pk_fma_f32 v[16:17], v[0:1], v[150:151], v[14:15] neg_lo:[0,0,1] neg_hi:[0,0,1]
	v_pk_fma_f32 v[14:15], v[0:1], v[150:151], v[14:15] op_sel_hi:[1,0,1]
	v_mov_b32_e32 v17, v15
	v_pk_add_f32 v[150:151], v[16:17], v[32:33]
	s_nop 0
	v_mov_b32_e32 v6, v151
	s_cmp_le_u32 s36, 24
	s_cbranch_scc1 .Ls5p_done_a
	s_waitcnt vmcnt(7)
	v_pk_mul_f32 v[14:15], v[4:5], v[6:7] op_sel_hi:[1,0]
	v_pk_fma_f32 v[16:17], v[0:1], v[150:151], v[14:15] neg_lo:[0,0,1] neg_hi:[0,0,1]
	v_pk_fma_f32 v[14:15], v[0:1], v[150:151], v[14:15] op_sel_hi:[1,0,1]
	v_mov_b32_e32 v17, v15
	v_pk_add_f32 v[150:151], v[16:17], v[34:35]
	s_nop 0
	v_mov_b32_e32 v6, v151
	s_cmp_le_u32 s36, 25
	s_cbranch_scc1 .Ls5p_done_a
	s_waitcnt vmcnt(6)
	v_pk_mul_f32 v[14:15], v[4:5], v[6:7] op_sel_hi:[1,0]
	v_pk_fma_f32 v[16:17], v[0:1], v[150:151], v[14:15] neg_lo:[0,0,1] neg_hi:[0,0,1]
	v_pk_fma_f32 v[14:15], v[0:1], v[150:151], v[14:15] op_sel_hi:[1,0,1]
	v_mov_b32_e32 v17, v15
	v_pk_add_f32 v[150:151], v[16:17], v[36:37]
	s_nop 0
	v_mov_b32_e32 v6, v151
	s_cmp_le_u32 s36, 26
	s_cbranch_scc1 .Ls5p_done_a
	s_waitcnt vmcnt(5)
	v_pk_mul_f32 v[14:15], v[4:5], v[6:7] op_sel_hi:[1,0]
	v_pk_fma_f32 v[16:17], v[0:1], v[150:151], v[14:15] neg_lo:[0,0,1] neg_hi:[0,0,1]
	v_pk_fma_f32 v[14:15], v[0:1], v[150:151], v[14:15] op_sel_hi:[1,0,1]
	v_mov_b32_e32 v17, v15
	v_pk_add_f32 v[150:151], v[16:17], v[38:39]
	s_nop 0
	v_mov_b32_e32 v6, v151
	s_cmp_le_u32 s36, 27
	s_cbranch_scc1 .Ls5p_done_a
	s_waitcnt vmcnt(4)
	v_pk_mul_f32 v[14:15], v[4:5], v[6:7] op_sel_hi:[1,0]
	v_pk_fma_f32 v[16:17], v[0:1], v[150:151], v[14:15] neg_lo:[0,0,1] neg_hi:[0,0,1]
	v_pk_fma_f32 v[14:15], v[0:1], v[150:151], v[14:15] op_sel_hi:[1,0,1]
	v_mov_b32_e32 v17, v15
	v_pk_add_f32 v[150:151], v[16:17], v[40:41]
	s_nop 0
	v_mov_b32_e32 v6, v151
	s_cmp_le_u32 s36, 28
	s_cbranch_scc1 .Ls5p_done_a
	s_waitcnt vmcnt(3)
	v_pk_mul_f32 v[14:15], v[4:5], v[6:7] op_sel_hi:[1,0]
	v_pk_fma_f32 v[16:17], v[0:1], v[150:151], v[14:15] neg_lo:[0,0,1] neg_hi:[0,0,1]
	v_pk_fma_f32 v[14:15], v[0:1], v[150:151], v[14:15] op_sel_hi:[1,0,1]
	v_mov_b32_e32 v17, v15
	v_pk_add_f32 v[150:151], v[16:17], v[42:43]
	s_nop 0
	v_mov_b32_e32 v6, v151
	s_cmp_le_u32 s36, 29
	s_cbranch_scc1 .Ls5p_done_a
	s_waitcnt vmcnt(2)
	v_pk_mul_f32 v[14:15], v[4:5], v[6:7] op_sel_hi:[1,0]
	v_pk_fma_f32 v[16:17], v[0:1], v[150:151], v[14:15] neg_lo:[0,0,1] neg_hi:[0,0,1]
	v_pk_fma_f32 v[14:15], v[0:1], v[150:151], v[14:15] op_sel_hi:[1,0,1]
	v_mov_b32_e32 v17, v15
	v_pk_add_f32 v[150:151], v[16:17], v[44:45]
	s_nop 0
	v_mov_b32_e32 v6, v151
	s_cmp_le_u32 s36, 30
	s_cbranch_scc1 .Ls5p_done_a
	s_waitcnt vmcnt(1)
	v_pk_mul_f32 v[14:15], v[4:5], v[6:7] op_sel_hi:[1,0]
	v_pk_fma_f32 v[16:17], v[0:1], v[150:151], v[14:15] neg_lo:[0,0,1] neg_hi:[0,0,1]
	v_pk_fma_f32 v[14:15], v[0:1], v[150:151], v[14:15] op_sel_hi:[1,0,1]
	v_mov_b32_e32 v17, v15
	v_pk_add_f32 v[150:151], v[16:17], v[46:47]
	s_nop 0
	v_mov_b32_e32 v6, v151
	s_cmp_le_u32 s36, 31
	s_cbranch_scc1 .Ls5p_done_a
	s_waitcnt vmcnt(0)
	v_pk_mul_f32 v[14:15], v[4:5], v[6:7] op_sel_hi:[1,0]
	v_pk_fma_f32 v[16:17], v[0:1], v[150:151], v[14:15] neg_lo:[0,0,1] neg_hi:[0,0,1]
	v_pk_fma_f32 v[14:15], v[0:1], v[150:151], v[14:15] op_sel_hi:[1,0,1]
	v_mov_b32_e32 v17, v15
	v_pk_add_f32 v[150:151], v[16:17], v[48:49]
	s_nop 0
	v_mov_b32_e32 v6, v151
.Ls5p_done_a:
	s_waitcnt vmcnt(0)
.LBB0_521:
	s_or_b64 exec, exec, s[34:35]
	v_lshlrev_b32_e32 v2, 8, v9
	v_or_b32_e32 v0, v2, v176
	v_ashrrev_i32_e32 v1, 31, v0
	v_lshlrev_b64 v[0:1], 11, v[0:1]
	v_lshl_add_u64 v[0:1], s[26:27], 0, v[0:1]
	v_lshlrev_b32_e32 v124, 1, v7
	v_lshl_add_u64 v[0:1], v[0:1], 0, v[124:125]
	v_mov_b32_e32 v141, v125
	v_lshl_add_u64 v[0:1], v[0:1], 0, v[140:141]
	global_load_dwordx4 v[120:123], v[0:1], off nt
	s_waitcnt vmcnt(10)
	v_bfe_u32 v0, v8, 16, 1
	v_add3_u32 v0, v8, v0, s33
	v_lshrrev_b32_e32 v0, 16, v0
	v_cndmask_b32_e64 v1, 0, v0, s[0:1]
	v_cndmask_b32_e64 v3, 0, v0, s[4:5]
	v_cndmask_b32_e64 v4, 0, v0, s[22:23]
	v_cndmask_b32_e64 v5, 0, v0, s[8:9]
	v_cndmask_b32_e64 v6, 0, v0, s[6:7]
	v_cndmask_b32_e64 v7, 0, v0, s[12:13]
	v_cndmask_b32_e64 v8, 0, v0, s[10:11]
	v_cndmask_b32_e64 v0, 0, v0, s[14:15]
	v_lshl_add_u64 v[144:145], v[134:135], 0, v[124:125]
	v_lshl_add_u64 v[146:147], s[88:89], 0, v[124:125]
	v_perm_b32 v115, v0, v8, s38
	v_perm_b32 v114, v7, v6, s38
	v_perm_b32 v113, v5, v4, s38
	v_perm_b32 v112, v3, v1, s38
	s_waitcnt vmcnt(1)
	v_mov_b32_e32 v124, v143
	v_pk_mov_b32 v[148:149], v[142:143], v[142:143] op_sel:[1,0]
	v_or_b32_e32 v141, v129, v2
	v_or_b32_e32 v225, v223, v2
	s_mov_b32 s36, 0
	s_waitcnt vmcnt(0)
	v_mov_b64_e32 v[116:117], v[120:121]
	v_mov_b64_e32 v[118:119], v[122:123]
	s_branch .LBB0_523

.LBB0_534:
	global_load_dwordx4 v[112:115], v[124:125], off offset:3072
	global_load_dwordx4 v[116:119], v[124:125], off offset:2048
	global_load_dwordx4 v[120:123], v[124:125], off offset:1024
	s_nop 0
	global_load_dwordx4 v[124:127], v[124:125], off
	s_waitcnt vmcnt(6)
	v_mfma_f32_32x32x16_bf16 v[0:15], v[68:71], v[108:111], 0
	v_add_u32_e32 v248, v176, v246
	v_add_u32_e32 v136, 0xffffff00, v248
	v_cmp_lt_i32_e32 vcc, v136, v242
	v_mfma_f32_32x32x16_bf16 v[0:15], v[64:67], v[100:103], v[0:15]
	v_mfma_f32_32x32x16_bf16 v[0:15], v[52:55], v[92:95], v[0:15]
	v_mfma_f32_32x32x16_bf16 v[0:15], v[48:51], v[84:87], v[0:15]
	s_nop 11
	v_max_f32_e32 v0, 0, v0
	v_fma_f32 v0, v24, v0, 0
	v_max_f32_e32 v1, 0, v1
	v_max_f32_e32 v8, 0, v8
	v_fmac_f32_e32 v0, v25, v1
	v_fma_f32 v8, v40, v8, 0
	v_max_f32_e32 v1, 0, v9
	v_fmac_f32_e32 v8, v41, v1
	v_max_f32_e32 v1, 0, v2
	v_fmac_f32_e32 v0, v26, v1
	v_max_f32_e32 v1, 0, v10
	v_fmac_f32_e32 v8, v42, v1
	v_max_f32_e32 v1, 0, v3
	v_fmac_f32_e32 v0, v27, v1
	v_max_f32_e32 v1, 0, v11
	v_fmac_f32_e32 v8, v43, v1
	v_max_f32_e32 v1, 0, v4
	v_fmac_f32_e32 v0, v28, v1
	v_max_f32_e32 v1, 0, v12
	v_fmac_f32_e32 v8, v44, v1
	v_max_f32_e32 v1, 0, v5
	v_fmac_f32_e32 v0, v29, v1
	v_max_f32_e32 v1, 0, v13
	v_fmac_f32_e32 v8, v45, v1
	v_max_f32_e32 v1, 0, v6
	v_fmac_f32_e32 v0, v30, v1
	v_max_f32_e32 v1, 0, v14
	v_fmac_f32_e32 v8, v46, v1
	v_max_f32_e32 v1, 0, v7
	v_fmac_f32_e32 v0, v31, v1
	v_max_f32_e32 v1, 0, v15
	v_fmac_f32_e32 v8, v47, v1
	s_nop 1
	v_permlane32_swap_b32_e32 v0, v8
	s_and_saveexec_b64 s[26:27], vcc
	s_cbranch_execz .LBB0_539
	v_cmp_le_i32_e32 vcc, v136, v240
	s_and_saveexec_b64 s[30:31], vcc
	s_xor_b64 s[30:31], exec, s[30:31]
	s_cbranch_execz .LBB0_537
	v_add_f32_e32 v0, v0, v8
	v_add_f32_e32 v1, 4.0, v0
	v_mul_f32_e32 v1, 0x42000000, v1
	v_max_f32_e32 v1, 0, v1
	v_min_f32_e32 v1, 0x437f0000, v1
	v_cvt_i32_f32_e32 v1, v1
	v_ashrrev_i32_e32 v2, 31, v0
	v_bitop3_b32 v0, v2, v0, s77 bitop3:0x36
	ds_write_b32 v244, v0
	v_lshl_add_u32 v0, v1, 2, v143
	ds_add_u32 v0, v233 offset:2048

.LBB0_539:
	s_or_b64 exec, exec, s[26:27]
	v_add_u32_e32 v0, 0xffffff00, v246
	v_cmp_ge_i32_e32 vcc, s22, v0
	s_and_saveexec_b64 s[26:27], vcc
	s_cbranch_execz .LBB0_545
	s_waitcnt vmcnt(4)
	v_mfma_f32_32x32x16_bf16 v[0:15], v[76:79], v[108:111], 0
	v_cmp_lt_i32_e32 vcc, v136, v243
	v_mfma_f32_32x32x16_bf16 v[0:15], v[72:75], v[100:103], v[0:15]
	v_mfma_f32_32x32x16_bf16 v[0:15], v[60:63], v[92:95], v[0:15]
	v_mfma_f32_32x32x16_bf16 v[0:15], v[56:59], v[84:87], v[0:15]
	s_nop 11
	v_max_f32_e32 v0, 0, v0
	v_max_f32_e32 v84, 0, v1
	v_fma_f32 v0, v16, v0, 0
	v_max_f32_e32 v8, 0, v8
	v_max_f32_e32 v2, 0, v2
	v_fmac_f32_e32 v0, v17, v84
	v_max_f32_e32 v9, 0, v9
	v_max_f32_e32 v3, 0, v3
	v_fma_f32 v1, v32, v8, 0
	v_fmac_f32_e32 v0, v18, v2
	v_max_f32_e32 v10, 0, v10
	v_max_f32_e32 v4, 0, v4
	v_fmac_f32_e32 v1, v33, v9
	v_fmac_f32_e32 v0, v19, v3
	v_max_f32_e32 v11, 0, v11
	v_max_f32_e32 v5, 0, v5
	v_fmac_f32_e32 v1, v34, v10
	v_fmac_f32_e32 v0, v20, v4
	v_max_f32_e32 v12, 0, v12
	v_fmac_f32_e32 v1, v35, v11
	v_fmac_f32_e32 v0, v21, v5
	v_max_f32_e32 v2, 0, v6
	v_max_f32_e32 v13, 0, v13
	v_fmac_f32_e32 v1, v36, v12
	v_fmac_f32_e32 v0, v22, v2
	v_fmac_f32_e32 v1, v37, v13
	v_max_f32_e32 v2, 0, v14
	v_fmac_f32_e32 v1, v38, v2
	v_max_f32_e32 v2, 0, v7
	v_fmac_f32_e32 v0, v23, v2
	v_max_f32_e32 v2, 0, v15
	v_fmac_f32_e32 v1, v39, v2
	s_nop 1
	v_permlane32_swap_b32_e32 v0, v1
	s_and_b64 exec, exec, vcc
	s_cbranch_execz .LBB0_545
	v_cmp_le_i32_e32 vcc, v136, v241
	s_and_saveexec_b64 s[30:31], vcc
	s_xor_b64 s[30:31], exec, s[30:31]
	s_cbranch_execz .LBB0_543
	v_add_f32_e32 v0, v0, v1
	v_add_f32_e32 v1, 4.0, v0
	v_mul_f32_e32 v1, 0x42000000, v1
	v_max_f32_e32 v1, 0, v1
	v_min_f32_e32 v1, 0x437f0000, v1
	v_cvt_i32_f32_e32 v1, v1
	v_ashrrev_i32_e32 v2, 31, v0
	v_bitop3_b32 v0, v2, v0, s77 bitop3:0x36
	ds_write_b32 v245, v0
	v_lshl_add_u32 v0, v1, 2, v143
	ds_add_u32 v0, v233

.LBB0_545:
	s_or_b64 exec, exec, s[26:27]
	v_add_u32_e32 v249, -8, v247
	v_min_i32_e32 v136, s23, v249
	v_lshlrev_b64 v[0:1], 12, v[136:137]
	v_lshl_add_u64 v[0:1], v[150:151], 0, v[0:1]
	global_load_dwordx4 v[108:111], v[0:1], off
	global_load_dwordx4 v[100:103], v[0:1], off offset:1024
	global_load_dwordx4 v[92:95], v[0:1], off offset:2048
	global_load_dwordx4 v[84:87], v[0:1], off offset:3072
	v_add_u32_e32 v0, -16, v247
	v_cmp_ge_u32_e32 vcc, s23, v0
	s_and_saveexec_b64 s[26:27], vcc
	s_cbranch_execz .LBB0_557
	v_mfma_f32_32x32x16_bf16 v[0:15], v[68:71], v[104:107], 0
	v_add_u32_e32 v136, 0xffffff80, v248
	v_cmp_lt_i32_e32 vcc, v136, v242
	v_mfma_f32_32x32x16_bf16 v[0:15], v[64:67], v[96:99], v[0:15]
	s_waitcnt vmcnt(9)
	v_mfma_f32_32x32x16_bf16 v[0:15], v[52:55], v[88:91], v[0:15]
	s_waitcnt vmcnt(8)
	v_mfma_f32_32x32x16_bf16 v[0:15], v[48:51], v[80:83], v[0:15]
	s_nop 11
	v_max_f32_e32 v0, 0, v0
	v_max_f32_e32 v250, 0, v1
	v_fma_f32 v0, v24, v0, 0
	v_max_f32_e32 v8, 0, v8
	v_max_f32_e32 v2, 0, v2
	v_fmac_f32_e32 v0, v25, v250
	v_max_f32_e32 v9, 0, v9
	v_max_f32_e32 v3, 0, v3
	v_fma_f32 v1, v40, v8, 0
	v_fmac_f32_e32 v0, v26, v2
	v_max_f32_e32 v10, 0, v10
	v_max_f32_e32 v4, 0, v4
	v_fmac_f32_e32 v1, v41, v9
	v_fmac_f32_e32 v0, v27, v3
	v_max_f32_e32 v11, 0, v11
	v_max_f32_e32 v5, 0, v5
	v_fmac_f32_e32 v1, v42, v10
	v_fmac_f32_e32 v0, v28, v4
	v_max_f32_e32 v12, 0, v12
	v_fmac_f32_e32 v1, v43, v11
	v_fmac_f32_e32 v0, v29, v5
	v_max_f32_e32 v2, 0, v6
	v_max_f32_e32 v13, 0, v13
	v_fmac_f32_e32 v1, v44, v12
	v_fmac_f32_e32 v0, v30, v2
	v_fmac_f32_e32 v1, v45, v13
	v_max_f32_e32 v2, 0, v14
	v_fmac_f32_e32 v1, v46, v2
	v_max_f32_e32 v2, 0, v7
	v_fmac_f32_e32 v0, v31, v2
	v_max_f32_e32 v2, 0, v15
	v_fmac_f32_e32 v1, v47, v2
	s_nop 1
	v_permlane32_swap_b32_e32 v0, v1
	s_and_saveexec_b64 s[30:31], vcc
	s_cbranch_execz .LBB0_551
	v_cmp_le_i32_e32 vcc, v136, v240
	s_and_saveexec_b64 s[34:35], vcc
	s_xor_b64 s[34:35], exec, s[34:35]
	s_cbranch_execz .LBB0_549
	v_add_f32_e32 v0, v0, v1
	v_add_f32_e32 v1, 4.0, v0
	v_mul_f32_e32 v1, 0x42000000, v1
	v_max_f32_e32 v1, 0, v1
	v_min_f32_e32 v1, 0x437f0000, v1
	v_cvt_i32_f32_e32 v1, v1
	v_ashrrev_i32_e32 v2, 31, v0
	v_bitop3_b32 v0, v2, v0, s77 bitop3:0x36
	ds_write_b32 v244, v0 offset:512
	v_lshl_add_u32 v0, v1, 2, v143
	ds_add_u32 v0, v233 offset:2048

.LBB0_551:
	s_or_b64 exec, exec, s[30:31]
	v_add_u32_e32 v0, 0xffffff80, v246
	v_cmp_ge_i32_e32 vcc, s22, v0
	s_and_b64 exec, exec, vcc
	s_cbranch_execz .LBB0_557
	s_waitcnt vmcnt(8)
	v_mfma_f32_32x32x16_bf16 v[0:15], v[76:79], v[104:107], 0
	v_cmp_lt_i32_e32 vcc, v136, v243
	v_mfma_f32_32x32x16_bf16 v[0:15], v[72:75], v[96:99], v[0:15]
	v_mfma_f32_32x32x16_bf16 v[0:15], v[60:63], v[88:91], v[0:15]
	v_mfma_f32_32x32x16_bf16 v[0:15], v[56:59], v[80:83], v[0:15]
	s_nop 11
	v_max_f32_e32 v0, 0, v0
	v_max_f32_e32 v80, 0, v1
	v_fma_f32 v0, v16, v0, 0
	v_max_f32_e32 v8, 0, v8
	v_max_f32_e32 v2, 0, v2
	v_fmac_f32_e32 v0, v17, v80
	v_max_f32_e32 v9, 0, v9
	v_max_f32_e32 v3, 0, v3
	v_fma_f32 v1, v32, v8, 0
	v_fmac_f32_e32 v0, v18, v2
	v_max_f32_e32 v10, 0, v10
	v_max_f32_e32 v4, 0, v4
	v_fmac_f32_e32 v1, v33, v9
	v_fmac_f32_e32 v0, v19, v3
	v_max_f32_e32 v11, 0, v11
	v_max_f32_e32 v5, 0, v5
	v_fmac_f32_e32 v1, v34, v10
	v_fmac_f32_e32 v0, v20, v4
	v_max_f32_e32 v12, 0, v12
	v_fmac_f32_e32 v1, v35, v11
	v_fmac_f32_e32 v0, v21, v5
	v_max_f32_e32 v2, 0, v6
	v_max_f32_e32 v13, 0, v13
	v_fmac_f32_e32 v1, v36, v12
	v_fmac_f32_e32 v0, v22, v2
	v_fmac_f32_e32 v1, v37, v13
	v_max_f32_e32 v2, 0, v14
	v_fmac_f32_e32 v1, v38, v2
	v_max_f32_e32 v2, 0, v7
	v_fmac_f32_e32 v0, v23, v2
	v_max_f32_e32 v2, 0, v15
	v_fmac_f32_e32 v1, v39, v2
	s_nop 1
	v_permlane32_swap_b32_e32 v0, v1
	s_and_b64 exec, exec, vcc
	s_cbranch_execz .LBB0_557
	v_cmp_le_i32_e32 vcc, v136, v241
	s_and_saveexec_b64 s[30:31], vcc
	s_xor_b64 s[30:31], exec, s[30:31]
	s_cbranch_execz .LBB0_555
	v_add_f32_e32 v0, v0, v1
	v_add_f32_e32 v1, 4.0, v0
	v_mul_f32_e32 v1, 0x42000000, v1
	v_max_f32_e32 v1, 0, v1
	v_min_f32_e32 v1, 0x437f0000, v1
	v_cvt_i32_f32_e32 v1, v1
	v_ashrrev_i32_e32 v2, 31, v0
	v_bitop3_b32 v0, v2, v0, s77 bitop3:0x36
	ds_write_b32 v245, v0 offset:512
	v_lshl_add_u32 v0, v1, 2, v143
	ds_add_u32 v0, v233

.LBB0_557:
	s_or_b64 exec, exec, s[26:27]
	v_add_u32_e32 v0, -4, v247
	v_min_i32_e32 v136, s23, v0
	v_lshlrev_b64 v[0:1], 12, v[136:137]
	v_lshl_add_u64 v[0:1], v[150:151], 0, v[0:1]
	global_load_dwordx4 v[104:107], v[0:1], off
	global_load_dwordx4 v[96:99], v[0:1], off offset:1024
	global_load_dwordx4 v[88:91], v[0:1], off offset:2048
	global_load_dwordx4 v[80:83], v[0:1], off offset:3072
	v_add_u32_e32 v0, -12, v247
	v_cmp_ge_u32_e32 vcc, s23, v0
	s_and_saveexec_b64 s[26:27], vcc
	s_cbranch_execz .LBB0_533
	s_waitcnt vmcnt(8)
	v_mfma_f32_32x32x16_bf16 v[0:15], v[68:71], v[124:127], 0
	v_cmp_lt_i32_e32 vcc, v248, v242
	v_mfma_f32_32x32x16_bf16 v[0:15], v[64:67], v[120:123], v[0:15]
	v_mfma_f32_32x32x16_bf16 v[0:15], v[52:55], v[116:119], v[0:15]
	v_mfma_f32_32x32x16_bf16 v[0:15], v[48:51], v[112:115], v[0:15]
	s_nop 11
	v_max_f32_e32 v0, 0, v0
	v_max_f32_e32 v136, 0, v1
	v_fma_f32 v0, v24, v0, 0
	v_max_f32_e32 v8, 0, v8
	v_max_f32_e32 v2, 0, v2
	v_fmac_f32_e32 v0, v25, v136
	v_max_f32_e32 v9, 0, v9
	v_max_f32_e32 v3, 0, v3
	v_fma_f32 v1, v40, v8, 0
	v_fmac_f32_e32 v0, v26, v2
	v_max_f32_e32 v10, 0, v10
	v_max_f32_e32 v4, 0, v4
	v_fmac_f32_e32 v1, v41, v9
	v_fmac_f32_e32 v0, v27, v3
	v_max_f32_e32 v11, 0, v11
	v_max_f32_e32 v5, 0, v5
	v_fmac_f32_e32 v1, v42, v10
	v_fmac_f32_e32 v0, v28, v4
	v_max_f32_e32 v12, 0, v12
	v_fmac_f32_e32 v1, v43, v11
	v_fmac_f32_e32 v0, v29, v5
	v_max_f32_e32 v2, 0, v6
	v_max_f32_e32 v13, 0, v13
	v_fmac_f32_e32 v1, v44, v12
	v_fmac_f32_e32 v0, v30, v2
	v_fmac_f32_e32 v1, v45, v13
	v_max_f32_e32 v2, 0, v14
	v_fmac_f32_e32 v1, v46, v2
	v_max_f32_e32 v2, 0, v7
	v_fmac_f32_e32 v0, v31, v2
	v_max_f32_e32 v2, 0, v15
	v_fmac_f32_e32 v1, v47, v2
	s_nop 1
	v_permlane32_swap_b32_e32 v0, v1
	s_and_saveexec_b64 s[30:31], vcc
	s_cbranch_execz .LBB0_563
	v_cmp_le_i32_e32 vcc, v248, v240
	s_and_saveexec_b64 s[34:35], vcc
	s_xor_b64 s[34:35], exec, s[34:35]
	s_cbranch_execz .LBB0_561
	v_add_f32_e32 v0, v0, v1
	v_add_f32_e32 v1, 4.0, v0
	v_mul_f32_e32 v1, 0x42000000, v1
	v_max_f32_e32 v1, 0, v1
	v_min_f32_e32 v1, 0x437f0000, v1
	v_cvt_i32_f32_e32 v1, v1
	v_ashrrev_i32_e32 v2, 31, v0
	v_bitop3_b32 v0, v2, v0, s77 bitop3:0x36
	ds_write_b32 v244, v0 offset:1024
	v_lshl_add_u32 v0, v1, 2, v143
	ds_add_u32 v0, v233 offset:2048

.LBB0_563:
	s_or_b64 exec, exec, s[30:31]
	v_cmp_ge_i32_e32 vcc, s22, v246
	s_and_b64 exec, exec, vcc
	s_cbranch_execz .LBB0_533
	v_mfma_f32_32x32x16_bf16 v[0:15], v[76:79], v[124:127], 0
	v_cmp_lt_i32_e32 vcc, v248, v243
	v_mfma_f32_32x32x16_bf16 v[0:15], v[72:75], v[120:123], v[0:15]
	v_mfma_f32_32x32x16_bf16 v[0:15], v[60:63], v[116:119], v[0:15]
	v_mfma_f32_32x32x16_bf16 v[0:15], v[56:59], v[112:115], v[0:15]
	s_nop 11
	v_max_f32_e32 v0, 0, v0
	v_max_f32_e32 v112, 0, v1
	v_fma_f32 v0, v16, v0, 0
	v_max_f32_e32 v8, 0, v8
	v_max_f32_e32 v2, 0, v2
	v_fmac_f32_e32 v0, v17, v112
	v_max_f32_e32 v9, 0, v9
	v_max_f32_e32 v3, 0, v3
	v_fma_f32 v1, v32, v8, 0
	v_fmac_f32_e32 v0, v18, v2
	v_max_f32_e32 v10, 0, v10
	v_max_f32_e32 v4, 0, v4
	v_fmac_f32_e32 v1, v33, v9
	v_fmac_f32_e32 v0, v19, v3
	v_max_f32_e32 v11, 0, v11
	v_max_f32_e32 v5, 0, v5
	v_fmac_f32_e32 v1, v34, v10
	v_fmac_f32_e32 v0, v20, v4
	v_max_f32_e32 v12, 0, v12
	v_fmac_f32_e32 v1, v35, v11
	v_fmac_f32_e32 v0, v21, v5
	v_max_f32_e32 v2, 0, v6
	v_max_f32_e32 v13, 0, v13
	v_fmac_f32_e32 v1, v36, v12
	v_fmac_f32_e32 v0, v22, v2
	v_fmac_f32_e32 v1, v37, v13
	v_max_f32_e32 v2, 0, v14
	v_fmac_f32_e32 v1, v38, v2
	v_max_f32_e32 v2, 0, v7
	v_fmac_f32_e32 v0, v23, v2
	v_max_f32_e32 v2, 0, v15
	v_fmac_f32_e32 v1, v39, v2
	s_nop 1
	v_permlane32_swap_b32_e32 v0, v1
	s_and_b64 exec, exec, vcc
	s_cbranch_execz .LBB0_533
	v_cmp_le_i32_e32 vcc, v248, v241
	s_and_saveexec_b64 s[30:31], vcc
	s_xor_b64 s[30:31], exec, s[30:31]
	s_cbranch_execz .LBB0_567
	v_add_f32_e32 v0, v0, v1
	v_add_f32_e32 v1, 4.0, v0
	v_mul_f32_e32 v1, 0x42000000, v1
	v_max_f32_e32 v1, 0, v1
	v_min_f32_e32 v1, 0x437f0000, v1
	v_cvt_i32_f32_e32 v1, v1
	v_ashrrev_i32_e32 v2, 31, v0
	v_bitop3_b32 v0, v2, v0, s77 bitop3:0x36
	ds_write_b32 v245, v0 offset:1024
	v_lshl_add_u32 v0, v1, 2, v143
	ds_add_u32 v0, v233

.LBB0_796:
	v_lshl_add_u32 v4, s39, 2, v187
	v_and_b32_e32 v2, 63, v4
	v_lshlrev_b32_e32 v124, 12, v2
	v_lshl_add_u64 v[0:1], v[136:137], 0, v[124:125]
	s_waitcnt vmcnt(5)
	v_lshlrev_b32_e32 v8, 4, v2
	global_load_dwordx4 v[64:67], v[0:1], off
	global_load_dwordx4 v[68:71], v[0:1], off offset:1024
	global_load_dwordx4 v[72:75], v[0:1], off offset:2048
	global_load_dwordx4 v[76:79], v[0:1], off offset:3072
	v_or_b32_e32 v1, v8, v175
	v_lshlrev_b32_e32 v124, 13, v2
	v_lshl_or_b32 v0, v2, 6, v129
	v_lshlrev_b32_e32 v1, 2, v1
	v_lshl_add_u64 v[2:3], v[126:127], 0, v[124:125]
	v_lshlrev_b32_e32 v0, 3, v0
	global_load_dword v7, v1, s[82:83]
	global_load_dwordx4 v[80:83], v[2:3], off
	global_load_dwordx4 v[84:87], v[2:3], off offset:32
	global_load_dwordx4 v[88:91], v[2:3], off offset:64
	global_load_dwordx4 v[92:95], v[2:3], off offset:96
	global_load_dwordx4 v[96:99], v[2:3], off offset:128
	global_load_dwordx4 v[100:103], v[2:3], off offset:160
	global_load_dwordx4 v[104:107], v[2:3], off offset:192
	global_load_dwordx4 v[108:111], v[2:3], off offset:224
	global_load_dwordx2 v[140:141], v0, s[24:25]
	v_ashrrev_i32_e32 v9, 6, v4
	v_mov_b32_e32 v124, v125
	v_cmp_lt_i32_e32 vcc, 0, v9
	v_mov_b64_e32 v[148:149], v[124:125]
	s_and_saveexec_b64 s[34:35], vcc
	s_cbranch_execz .LBB0_800
	global_load_dwordx2 v[0:1], v0, s[28:29]
	v_and_b32_e32 v2, 63, v131
	v_lshlrev_b32_e32 v124, 9, v2
	v_mov_b32_e32 v148, 0
	v_lshl_add_u64 v[2:3], v[138:139], 0, v[124:125]
	v_mov_b32_e32 v6, 0
	v_readfirstlane_b32 s36, v9
	global_load_dwordx2 v[18:19], v[2:3], off
	v_lshl_add_u64 v[2:3], v[2:3], 0, s[30:31]
	global_load_dwordx2 v[20:21], v[2:3], off
	v_lshl_add_u64 v[2:3], v[2:3], 0, s[30:31]
	global_load_dwordx2 v[22:23], v[2:3], off
	v_lshl_add_u64 v[2:3], v[2:3], 0, s[30:31]
	global_load_dwordx2 v[24:25], v[2:3], off
	v_lshl_add_u64 v[2:3], v[2:3], 0, s[30:31]
	global_load_dwordx2 v[26:27], v[2:3], off
	v_lshl_add_u64 v[2:3], v[2:3], 0, s[30:31]
	global_load_dwordx2 v[28:29], v[2:3], off
	v_lshl_add_u64 v[2:3], v[2:3], 0, s[30:31]
	global_load_dwordx2 v[30:31], v[2:3], off
	v_lshl_add_u64 v[2:3], v[2:3], 0, s[30:31]
	global_load_dwordx2 v[32:33], v[2:3], off
	v_lshl_add_u64 v[2:3], v[2:3], 0, s[30:31]
	global_load_dwordx2 v[34:35], v[2:3], off
	v_lshl_add_u64 v[2:3], v[2:3], 0, s[30:31]
	global_load_dwordx2 v[36:37], v[2:3], off
	v_lshl_add_u64 v[2:3], v[2:3], 0, s[30:31]
	global_load_dwordx2 v[38:39], v[2:3], off
	v_lshl_add_u64 v[2:3], v[2:3], 0, s[30:31]
	global_load_dwordx2 v[40:41], v[2:3], off
	v_lshl_add_u64 v[2:3], v[2:3], 0, s[30:31]
	global_load_dwordx2 v[42:43], v[2:3], off
	v_lshl_add_u64 v[2:3], v[2:3], 0, s[30:31]
	global_load_dwordx2 v[44:45], v[2:3], off
	v_lshl_add_u64 v[2:3], v[2:3], 0, s[30:31]
	global_load_dwordx2 v[46:47], v[2:3], off
	v_lshl_add_u64 v[2:3], v[2:3], 0, s[30:31]
	global_load_dwordx2 v[48:49], v[2:3], off
	v_lshl_add_u64 v[2:3], v[2:3], 0, s[30:31]
	s_waitcnt vmcnt(16)
	v_pk_mov_b32 v[4:5], v[0:1], v[0:1] op_sel:[1,0]
	s_waitcnt vmcnt(15)
	v_pk_mul_f32 v[14:15], v[4:5], v[6:7] op_sel_hi:[1,0]
	v_pk_fma_f32 v[16:17], v[0:1], v[148:149], v[14:15] neg_lo:[0,0,1] neg_hi:[0,0,1]
	v_pk_fma_f32 v[14:15], v[0:1], v[148:149], v[14:15] op_sel_hi:[1,0,1]
	v_mov_b32_e32 v17, v15
	v_pk_add_f32 v[148:149], v[16:17], v[18:19]
	s_nop 0
	v_mov_b32_e32 v6, v149
	s_cmp_le_u32 s36, 1
	s_cbranch_scc1 .Ls5p_done_b
	s_waitcnt vmcnt(14)
	v_pk_mul_f32 v[14:15], v[4:5], v[6:7] op_sel_hi:[1,0]
	v_pk_fma_f32 v[16:17], v[0:1], v[148:149], v[14:15] neg_lo:[0,0,1] neg_hi:[0,0,1]
	v_pk_fma_f32 v[14:15], v[0:1], v[148:149], v[14:15] op_sel_hi:[1,0,1]
	v_mov_b32_e32 v17, v15
	v_pk_add_f32 v[148:149], v[16:17], v[20:21]
	s_nop 0
	v_mov_b32_e32 v6, v149
	s_cmp_le_u32 s36, 2
	s_cbranch_scc1 .Ls5p_done_b
	s_waitcnt vmcnt(13)
	v_pk_mul_f32 v[14:15], v[4:5], v[6:7] op_sel_hi:[1,0]
	v_pk_fma_f32 v[16:17], v[0:1], v[148:149], v[14:15] neg_lo:[0,0,1] neg_hi:[0,0,1]
	v_pk_fma_f32 v[14:15], v[0:1], v[148:149], v[14:15] op_sel_hi:[1,0,1]
	v_mov_b32_e32 v17, v15
	v_pk_add_f32 v[148:149], v[16:17], v[22:23]
	s_nop 0
	v_mov_b32_e32 v6, v149
	s_cmp_le_u32 s36, 3
	s_cbranch_scc1 .Ls5p_done_b
	s_waitcnt vmcnt(12)
	v_pk_mul_f32 v[14:15], v[4:5], v[6:7] op_sel_hi:[1,0]
	v_pk_fma_f32 v[16:17], v[0:1], v[148:149], v[14:15] neg_lo:[0,0,1] neg_hi:[0,0,1]
	v_pk_fma_f32 v[14:15], v[0:1], v[148:149], v[14:15] op_sel_hi:[1,0,1]
	v_mov_b32_e32 v17, v15
	v_pk_add_f32 v[148:149], v[16:17], v[24:25]
	s_nop 0
	v_mov_b32_e32 v6, v149
	s_cmp_le_u32 s36, 4
	s_cbranch_scc1 .Ls5p_done_b
	s_waitcnt vmcnt(11)
	v_pk_mul_f32 v[14:15], v[4:5], v[6:7] op_sel_hi:[1,0]
	v_pk_fma_f32 v[16:17], v[0:1], v[148:149], v[14:15] neg_lo:[0,0,1] neg_hi:[0,0,1]
	v_pk_fma_f32 v[14:15], v[0:1], v[148:149], v[14:15] op_sel_hi:[1,0,1]
	v_mov_b32_e32 v17, v15
	v_pk_add_f32 v[148:149], v[16:17], v[26:27]
	s_nop 0
	v_mov_b32_e32 v6, v149
	s_cmp_le_u32 s36, 5
	s_cbranch_scc1 .Ls5p_done_b
	s_waitcnt vmcnt(10)
	v_pk_mul_f32 v[14:15], v[4:5], v[6:7] op_sel_hi:[1,0]
	v_pk_fma_f32 v[16:17], v[0:1], v[148:149], v[14:15] neg_lo:[0,0,1] neg_hi:[0,0,1]
	v_pk_fma_f32 v[14:15], v[0:1], v[148:149], v[14:15] op_sel_hi:[1,0,1]
	v_mov_b32_e32 v17, v15
	v_pk_add_f32 v[148:149], v[16:17], v[28:29]
	s_nop 0
	v_mov_b32_e32 v6, v149
	s_cmp_le_u32 s36, 6
	s_cbranch_scc1 .Ls5p_done_b
	s_waitcnt vmcnt(9)
	v_pk_mul_f32 v[14:15], v[4:5], v[6:7] op_sel_hi:[1,0]
	v_pk_fma_f32 v[16:17], v[0:1], v[148:149], v[14:15] neg_lo:[0,0,1] neg_hi:[0,0,1]
	v_pk_fma_f32 v[14:15], v[0:1], v[148:149], v[14:15] op_sel_hi:[1,0,1]
	v_mov_b32_e32 v17, v15
	v_pk_add_f32 v[148:149], v[16:17], v[30:31]
	s_nop 0
	v_mov_b32_e32 v6, v149
	s_cmp_le_u32 s36, 7
	s_cbranch_scc1 .Ls5p_done_b
	s_waitcnt vmcnt(8)
	v_pk_mul_f32 v[14:15], v[4:5], v[6:7] op_sel_hi:[1,0]
	v_pk_fma_f32 v[16:17], v[0:1], v[148:149], v[14:15] neg_lo:[0,0,1] neg_hi:[0,0,1]
	v_pk_fma_f32 v[14:15], v[0:1], v[148:149], v[14:15] op_sel_hi:[1,0,1]
	v_mov_b32_e32 v17, v15
	v_pk_add_f32 v[148:149], v[16:17], v[32:33]
	s_nop 0
	v_mov_b32_e32 v6, v149
	s_cmp_le_u32 s36, 8
	s_cbranch_scc1 .Ls5p_done_b
	s_waitcnt vmcnt(7)
	v_pk_mul_f32 v[14:15], v[4:5], v[6:7] op_sel_hi:[1,0]
	v_pk_fma_f32 v[16:17], v[0:1], v[148:149], v[14:15] neg_lo:[0,0,1] neg_hi:[0,0,1]
	v_pk_fma_f32 v[14:15], v[0:1], v[148:149], v[14:15] op_sel_hi:[1,0,1]
	v_mov_b32_e32 v17, v15
	v_pk_add_f32 v[148:149], v[16:17], v[34:35]
	s_nop 0
	v_mov_b32_e32 v6, v149
	s_cmp_le_u32 s36, 9
	s_cbranch_scc1 .Ls5p_done_b
	s_waitcnt vmcnt(6)
	v_pk_mul_f32 v[14:15], v[4:5], v[6:7] op_sel_hi:[1,0]
	v_pk_fma_f32 v[16:17], v[0:1], v[148:149], v[14:15] neg_lo:[0,0,1] neg_hi:[0,0,1]
	v_pk_fma_f32 v[14:15], v[0:1], v[148:149], v[14:15] op_sel_hi:[1,0,1]
	v_mov_b32_e32 v17, v15
	v_pk_add_f32 v[148:149], v[16:17], v[36:37]
	s_nop 0
	v_mov_b32_e32 v6, v149
	s_cmp_le_u32 s36, 10
	s_cbranch_scc1 .Ls5p_done_b
	s_waitcnt vmcnt(5)
	v_pk_mul_f32 v[14:15], v[4:5], v[6:7] op_sel_hi:[1,0]
	v_pk_fma_f32 v[16:17], v[0:1], v[148:149], v[14:15] neg_lo:[0,0,1] neg_hi:[0,0,1]
	v_pk_fma_f32 v[14:15], v[0:1], v[148:149], v[14:15] op_sel_hi:[1,0,1]
	v_mov_b32_e32 v17, v15
	v_pk_add_f32 v[148:149], v[16:17], v[38:39]
	s_nop 0
	v_mov_b32_e32 v6, v149
	s_cmp_le_u32 s36, 11
	s_cbranch_scc1 .Ls5p_done_b
	s_waitcnt vmcnt(4)
	v_pk_mul_f32 v[14:15], v[4:5], v[6:7] op_sel_hi:[1,0]
	v_pk_fma_f32 v[16:17], v[0:1], v[148:149], v[14:15] neg_lo:[0,0,1] neg_hi:[0,0,1]
	v_pk_fma_f32 v[14:15], v[0:1], v[148:149], v[14:15] op_sel_hi:[1,0,1]
	v_mov_b32_e32 v17, v15
	v_pk_add_f32 v[148:149], v[16:17], v[40:41]
	s_nop 0
	v_mov_b32_e32 v6, v149
	s_cmp_le_u32 s36, 12
	s_cbranch_scc1 .Ls5p_done_b
	s_waitcnt vmcnt(3)
	v_pk_mul_f32 v[14:15], v[4:5], v[6:7] op_sel_hi:[1,0]
	v_pk_fma_f32 v[16:17], v[0:1], v[148:149], v[14:15] neg_lo:[0,0,1] neg_hi:[0,0,1]
	v_pk_fma_f32 v[14:15], v[0:1], v[148:149], v[14:15] op_sel_hi:[1,0,1]
	v_mov_b32_e32 v17, v15
	v_pk_add_f32 v[148:149], v[16:17], v[42:43]
	s_nop 0
	v_mov_b32_e32 v6, v149
	s_cmp_le_u32 s36, 13
	s_cbranch_scc1 .Ls5p_done_b
	s_waitcnt vmcnt(2)
	v_pk_mul_f32 v[14:15], v[4:5], v[6:7] op_sel_hi:[1,0]
	v_pk_fma_f32 v[16:17], v[0:1], v[148:149], v[14:15] neg_lo:[0,0,1] neg_hi:[0,0,1]
	v_pk_fma_f32 v[14:15], v[0:1], v[148:149], v[14:15] op_sel_hi:[1,0,1]
	v_mov_b32_e32 v17, v15
	v_pk_add_f32 v[148:149], v[16:17], v[44:45]
	s_nop 0
	v_mov_b32_e32 v6, v149
	s_cmp_le_u32 s36, 14
	s_cbranch_scc1 .Ls5p_done_b
	s_waitcnt vmcnt(1)
	v_pk_mul_f32 v[14:15], v[4:5], v[6:7] op_sel_hi:[1,0]
	v_pk_fma_f32 v[16:17], v[0:1], v[148:149], v[14:15] neg_lo:[0,0,1] neg_hi:[0,0,1]
	v_pk_fma_f32 v[14:15], v[0:1], v[148:149], v[14:15] op_sel_hi:[1,0,1]
	v_mov_b32_e32 v17, v15
	v_pk_add_f32 v[148:149], v[16:17], v[46:47]
	s_nop 0
	v_mov_b32_e32 v6, v149
	s_cmp_le_u32 s36, 15
	s_cbranch_scc1 .Ls5p_done_b
	s_waitcnt vmcnt(0)
	v_pk_mul_f32 v[14:15], v[4:5], v[6:7] op_sel_hi:[1,0]
	v_pk_fma_f32 v[16:17], v[0:1], v[148:149], v[14:15] neg_lo:[0,0,1] neg_hi:[0,0,1]
	v_pk_fma_f32 v[14:15], v[0:1], v[148:149], v[14:15] op_sel_hi:[1,0,1]
	v_mov_b32_e32 v17, v15
	v_pk_add_f32 v[148:149], v[16:17], v[48:49]
	s_nop 0
	v_mov_b32_e32 v6, v149
	s_cmp_le_u32 s36, 16
	s_cbranch_scc1 .Ls5p_done_b
	global_load_dwordx2 v[18:19], v[2:3], off
	v_lshl_add_u64 v[2:3], v[2:3], 0, s[30:31]
	global_load_dwordx2 v[20:21], v[2:3], off
	v_lshl_add_u64 v[2:3], v[2:3], 0, s[30:31]
	global_load_dwordx2 v[22:23], v[2:3], off
	v_lshl_add_u64 v[2:3], v[2:3], 0, s[30:31]
	global_load_dwordx2 v[24:25], v[2:3], off
	v_lshl_add_u64 v[2:3], v[2:3], 0, s[30:31]
	global_load_dwordx2 v[26:27], v[2:3], off
	v_lshl_add_u64 v[2:3], v[2:3], 0, s[30:31]
	global_load_dwordx2 v[28:29], v[2:3], off
	v_lshl_add_u64 v[2:3], v[2:3], 0, s[30:31]
	global_load_dwordx2 v[30:31], v[2:3], off
	v_lshl_add_u64 v[2:3], v[2:3], 0, s[30:31]
	global_load_dwordx2 v[32:33], v[2:3], off
	v_lshl_add_u64 v[2:3], v[2:3], 0, s[30:31]
	global_load_dwordx2 v[34:35], v[2:3], off
	v_lshl_add_u64 v[2:3], v[2:3], 0, s[30:31]
	global_load_dwordx2 v[36:37], v[2:3], off
	v_lshl_add_u64 v[2:3], v[2:3], 0, s[30:31]
	global_load_dwordx2 v[38:39], v[2:3], off
	v_lshl_add_u64 v[2:3], v[2:3], 0, s[30:31]
	global_load_dwordx2 v[40:41], v[2:3], off
	v_lshl_add_u64 v[2:3], v[2:3], 0, s[30:31]
	global_load_dwordx2 v[42:43], v[2:3], off
	v_lshl_add_u64 v[2:3], v[2:3], 0, s[30:31]
	global_load_dwordx2 v[44:45], v[2:3], off
	v_lshl_add_u64 v[2:3], v[2:3], 0, s[30:31]
	global_load_dwordx2 v[46:47], v[2:3], off
	v_lshl_add_u64 v[2:3], v[2:3], 0, s[30:31]
	global_load_dwordx2 v[48:49], v[2:3], off
	v_lshl_add_u64 v[2:3], v[2:3], 0, s[30:31]
	s_cmp_le_u32 s36, 16
	s_cbranch_scc1 .Ls5p_done_b
	s_waitcnt vmcnt(15)
	v_pk_mul_f32 v[14:15], v[4:5], v[6:7] op_sel_hi:[1,0]
	v_pk_fma_f32 v[16:17], v[0:1], v[148:149], v[14:15] neg_lo:[0,0,1] neg_hi:[0,0,1]
	v_pk_fma_f32 v[14:15], v[0:1], v[148:149], v[14:15] op_sel_hi:[1,0,1]
	v_mov_b32_e32 v17, v15
	v_pk_add_f32 v[148:149], v[16:17], v[18:19]
	s_nop 0
	v_mov_b32_e32 v6, v149
	s_cmp_le_u32 s36, 17
	s_cbranch_scc1 .Ls5p_done_b
	s_waitcnt vmcnt(14)
	v_pk_mul_f32 v[14:15], v[4:5], v[6:7] op_sel_hi:[1,0]
	v_pk_fma_f32 v[16:17], v[0:1], v[148:149], v[14:15] neg_lo:[0,0,1] neg_hi:[0,0,1]
	v_pk_fma_f32 v[14:15], v[0:1], v[148:149], v[14:15] op_sel_hi:[1,0,1]
	v_mov_b32_e32 v17, v15
	v_pk_add_f32 v[148:149], v[16:17], v[20:21]
	s_nop 0
	v_mov_b32_e32 v6, v149
	s_cmp_le_u32 s36, 18
	s_cbranch_scc1 .Ls5p_done_b
	s_waitcnt vmcnt(13)
	v_pk_mul_f32 v[14:15], v[4:5], v[6:7] op_sel_hi:[1,0]
	v_pk_fma_f32 v[16:17], v[0:1], v[148:149], v[14:15] neg_lo:[0,0,1] neg_hi:[0,0,1]
	v_pk_fma_f32 v[14:15], v[0:1], v[148:149], v[14:15] op_sel_hi:[1,0,1]
	v_mov_b32_e32 v17, v15
	v_pk_add_f32 v[148:149], v[16:17], v[22:23]
	s_nop 0
	v_mov_b32_e32 v6, v149
	s_cmp_le_u32 s36, 19
	s_cbranch_scc1 .Ls5p_done_b
	s_waitcnt vmcnt(12)
	v_pk_mul_f32 v[14:15], v[4:5], v[6:7] op_sel_hi:[1,0]
	v_pk_fma_f32 v[16:17], v[0:1], v[148:149], v[14:15] neg_lo:[0,0,1] neg_hi:[0,0,1]
	v_pk_fma_f32 v[14:15], v[0:1], v[148:149], v[14:15] op_sel_hi:[1,0,1]
	v_mov_b32_e32 v17, v15
	v_pk_add_f32 v[148:149], v[16:17], v[24:25]
	s_nop 0
	v_mov_b32_e32 v6, v149
	s_cmp_le_u32 s36, 20
	s_cbranch_scc1 .Ls5p_done_b
	s_waitcnt vmcnt(11)
	v_pk_mul_f32 v[14:15], v[4:5], v[6:7] op_sel_hi:[1,0]
	v_pk_fma_f32 v[16:17], v[0:1], v[148:149], v[14:15] neg_lo:[0,0,1] neg_hi:[0,0,1]
	v_pk_fma_f32 v[14:15], v[0:1], v[148:149], v[14:15] op_sel_hi:[1,0,1]
	v_mov_b32_e32 v17, v15
	v_pk_add_f32 v[148:149], v[16:17], v[26:27]
	s_nop 0
	v_mov_b32_e32 v6, v149
	s_cmp_le_u32 s36, 21
	s_cbranch_scc1 .Ls5p_done_b
	s_waitcnt vmcnt(10)
	v_pk_mul_f32 v[14:15], v[4:5], v[6:7] op_sel_hi:[1,0]
	v_pk_fma_f32 v[16:17], v[0:1], v[148:149], v[14:15] neg_lo:[0,0,1] neg_hi:[0,0,1]
	v_pk_fma_f32 v[14:15], v[0:1], v[148:149], v[14:15] op_sel_hi:[1,0,1]
	v_mov_b32_e32 v17, v15
	v_pk_add_f32 v[148:149], v[16:17], v[28:29]
	s_nop 0
	v_mov_b32_e32 v6, v149
	s_cmp_le_u32 s36, 22
	s_cbranch_scc1 .Ls5p_done_b
	s_waitcnt vmcnt(9)
	v_pk_mul_f32 v[14:15], v[4:5], v[6:7] op_sel_hi:[1,0]
	v_pk_fma_f32 v[16:17], v[0:1], v[148:149], v[14:15] neg_lo:[0,0,1] neg_hi:[0,0,1]
	v_pk_fma_f32 v[14:15], v[0:1], v[148:149], v[14:15] op_sel_hi:[1,0,1]
	v_mov_b32_e32 v17, v15
	v_pk_add_f32 v[148:149], v[16:17], v[30:31]
	s_nop 0
	v_mov_b32_e32 v6, v149
	s_cmp_le_u32 s36, 23
	s_cbranch_scc1 .Ls5p_done_b
	s_waitcnt vmcnt(8)
	v_pk_mul_f32 v[14:15], v[4:5], v[6:7] op_sel_hi:[1,0]
	v_pk_fma_f32 v[16:17], v[0:1], v[148:149], v[14:15] neg_lo:[0,0,1] neg_hi:[0,0,1]
	v_pk_fma_f32 v[14:15], v[0:1], v[148:149], v[14:15] op_sel_hi:[1,0,1]
	v_mov_b32_e32 v17, v15
	v_pk_add_f32 v[148:149], v[16:17], v[32:33]
	s_nop 0
	v_mov_b32_e32 v6, v149
	s_cmp_le_u32 s36, 24
	s_cbranch_scc1 .Ls5p_done_b
	s_waitcnt vmcnt(7)
	v_pk_mul_f32 v[14:15], v[4:5], v[6:7] op_sel_hi:[1,0]
	v_pk_fma_f32 v[16:17], v[0:1], v[148:149], v[14:15] neg_lo:[0,0,1] neg_hi:[0,0,1]
	v_pk_fma_f32 v[14:15], v[0:1], v[148:149], v[14:15] op_sel_hi:[1,0,1]
	v_mov_b32_e32 v17, v15
	v_pk_add_f32 v[148:149], v[16:17], v[34:35]
	s_nop 0
	v_mov_b32_e32 v6, v149
	s_cmp_le_u32 s36, 25
	s_cbranch_scc1 .Ls5p_done_b
	s_waitcnt vmcnt(6)
	v_pk_mul_f32 v[14:15], v[4:5], v[6:7] op_sel_hi:[1,0]
	v_pk_fma_f32 v[16:17], v[0:1], v[148:149], v[14:15] neg_lo:[0,0,1] neg_hi:[0,0,1]
	v_pk_fma_f32 v[14:15], v[0:1], v[148:149], v[14:15] op_sel_hi:[1,0,1]
	v_mov_b32_e32 v17, v15
	v_pk_add_f32 v[148:149], v[16:17], v[36:37]
	s_nop 0
	v_mov_b32_e32 v6, v149
	s_cmp_le_u32 s36, 26
	s_cbranch_scc1 .Ls5p_done_b
	s_waitcnt vmcnt(5)
	v_pk_mul_f32 v[14:15], v[4:5], v[6:7] op_sel_hi:[1,0]
	v_pk_fma_f32 v[16:17], v[0:1], v[148:149], v[14:15] neg_lo:[0,0,1] neg_hi:[0,0,1]
	v_pk_fma_f32 v[14:15], v[0:1], v[148:149], v[14:15] op_sel_hi:[1,0,1]
	v_mov_b32_e32 v17, v15
	v_pk_add_f32 v[148:149], v[16:17], v[38:39]
	s_nop 0
	v_mov_b32_e32 v6, v149
	s_cmp_le_u32 s36, 27
	s_cbranch_scc1 .Ls5p_done_b
	s_waitcnt vmcnt(4)
	v_pk_mul_f32 v[14:15], v[4:5], v[6:7] op_sel_hi:[1,0]
	v_pk_fma_f32 v[16:17], v[0:1], v[148:149], v[14:15] neg_lo:[0,0,1] neg_hi:[0,0,1]
	v_pk_fma_f32 v[14:15], v[0:1], v[148:149], v[14:15] op_sel_hi:[1,0,1]
	v_mov_b32_e32 v17, v15
	v_pk_add_f32 v[148:149], v[16:17], v[40:41]
	s_nop 0
	v_mov_b32_e32 v6, v149
	s_cmp_le_u32 s36, 28
	s_cbranch_scc1 .Ls5p_done_b
	s_waitcnt vmcnt(3)
	v_pk_mul_f32 v[14:15], v[4:5], v[6:7] op_sel_hi:[1,0]
	v_pk_fma_f32 v[16:17], v[0:1], v[148:149], v[14:15] neg_lo:[0,0,1] neg_hi:[0,0,1]
	v_pk_fma_f32 v[14:15], v[0:1], v[148:149], v[14:15] op_sel_hi:[1,0,1]
	v_mov_b32_e32 v17, v15
	v_pk_add_f32 v[148:149], v[16:17], v[42:43]
	s_nop 0
	v_mov_b32_e32 v6, v149
	s_cmp_le_u32 s36, 29
	s_cbranch_scc1 .Ls5p_done_b
	s_waitcnt vmcnt(2)
	v_pk_mul_f32 v[14:15], v[4:5], v[6:7] op_sel_hi:[1,0]
	v_pk_fma_f32 v[16:17], v[0:1], v[148:149], v[14:15] neg_lo:[0,0,1] neg_hi:[0,0,1]
	v_pk_fma_f32 v[14:15], v[0:1], v[148:149], v[14:15] op_sel_hi:[1,0,1]
	v_mov_b32_e32 v17, v15
	v_pk_add_f32 v[148:149], v[16:17], v[44:45]
	s_nop 0
	v_mov_b32_e32 v6, v149
	s_cmp_le_u32 s36, 30
	s_cbranch_scc1 .Ls5p_done_b
	s_waitcnt vmcnt(1)
	v_pk_mul_f32 v[14:15], v[4:5], v[6:7] op_sel_hi:[1,0]
	v_pk_fma_f32 v[16:17], v[0:1], v[148:149], v[14:15] neg_lo:[0,0,1] neg_hi:[0,0,1]
	v_pk_fma_f32 v[14:15], v[0:1], v[148:149], v[14:15] op_sel_hi:[1,0,1]
	v_mov_b32_e32 v17, v15
	v_pk_add_f32 v[148:149], v[16:17], v[46:47]
	s_nop 0
	v_mov_b32_e32 v6, v149
	s_cmp_le_u32 s36, 31
	s_cbranch_scc1 .Ls5p_done_b
	s_waitcnt vmcnt(0)
	v_pk_mul_f32 v[14:15], v[4:5], v[6:7] op_sel_hi:[1,0]
	v_pk_fma_f32 v[16:17], v[0:1], v[148:149], v[14:15] neg_lo:[0,0,1] neg_hi:[0,0,1]
	v_pk_fma_f32 v[14:15], v[0:1], v[148:149], v[14:15] op_sel_hi:[1,0,1]
	v_mov_b32_e32 v17, v15
	v_pk_add_f32 v[148:149], v[16:17], v[48:49]
	s_nop 0
	v_mov_b32_e32 v6, v149
.Ls5p_done_b:
	s_waitcnt vmcnt(0)
.LBB0_800:
	s_or_b64 exec, exec, s[34:35]
	v_lshlrev_b32_e32 v2, 8, v9
	v_or_b32_e32 v0, v2, v176
	v_ashrrev_i32_e32 v1, 31, v0
	v_lshlrev_b64 v[0:1], 11, v[0:1]
	v_lshl_add_u64 v[0:1], s[26:27], 0, v[0:1]
	v_lshlrev_b32_e32 v124, 1, v8
	v_lshl_add_u64 v[0:1], v[0:1], 0, v[124:125]
	v_mov_b32_e32 v133, v125
	v_lshl_add_u64 v[0:1], v[0:1], 0, v[132:133]
	global_load_dwordx4 v[120:123], v[0:1], off nt
	s_waitcnt vmcnt(10)
	v_bfe_u32 v0, v7, 16, 1
	v_add3_u32 v0, v7, v0, s33
	v_lshrrev_b32_e32 v0, 16, v0
	v_cndmask_b32_e64 v1, 0, v0, s[0:1]
	v_cndmask_b32_e64 v3, 0, v0, s[4:5]
	v_cndmask_b32_e64 v4, 0, v0, s[22:23]
	v_cndmask_b32_e64 v5, 0, v0, s[8:9]
	v_cndmask_b32_e64 v6, 0, v0, s[6:7]
	v_cndmask_b32_e64 v7, 0, v0, s[12:13]
	v_cndmask_b32_e64 v8, 0, v0, s[10:11]
	v_cndmask_b32_e64 v0, 0, v0, s[14:15]
	v_lshl_add_u64 v[142:143], v[134:135], 0, v[124:125]
	v_lshl_add_u64 v[144:145], s[88:89], 0, v[124:125]
	v_perm_b32 v115, v0, v8, s38
	v_perm_b32 v114, v7, v6, s38
	v_perm_b32 v113, v5, v4, s38
	v_perm_b32 v112, v3, v1, s38
	s_waitcnt vmcnt(1)
	v_mov_b32_e32 v124, v141
	v_pk_mov_b32 v[146:147], v[140:141], v[140:141] op_sel:[1,0]
	v_or_b32_e32 v133, v129, v2
	v_or_b32_e32 v222, v220, v2
	s_mov_b32 s36, 0
	s_waitcnt vmcnt(0)
	v_mov_b64_e32 v[116:117], v[120:121]
	v_mov_b64_e32 v[118:119], v[122:123]
	s_branch .LBB0_802
